# sample attention softmax: the 8 tokens' wave max / sum reductions interleaved with v_max_f32_dpp / v_add_f32_dpp (no DPP wait-state padding, ~33 fewer instructions per token)
# baseline (speedup 1.0000x reference)
.Lsm_qk:
	ds_read_b128 v[84:87], v32 offset:32
	ds_read_b128 v[88:91], v32 offset:48
	ds_read_b128 v[92:95], v33 offset:32
	ds_read_b128 v[96:99], v33 offset:48
	ds_read_b128 v[100:103], v34 offset:32
	ds_read_b128 v[104:107], v34 offset:48
	ds_read_b128 v[16:19], v15 offset:256
	ds_read_b128 v[20:23], v15 offset:272
	s_waitcnt lgkmcnt(8)
	v_fmac_f32_e32 v176, v60, v24
	v_fmac_f32_e32 v184, v68, v24
	v_fmac_f32_e32 v192, v76, v24
	v_fmac_f32_e32 v176, v61, v25
	v_fmac_f32_e32 v184, v69, v25
	v_fmac_f32_e32 v192, v77, v25
	v_fmac_f32_e32 v176, v62, v26
	v_fmac_f32_e32 v184, v70, v26
	v_fmac_f32_e32 v192, v78, v26
	v_fmac_f32_e32 v176, v63, v27
	v_fmac_f32_e32 v184, v71, v27
	v_fmac_f32_e32 v192, v79, v27
	v_fmac_f32_e32 v176, v64, v28
	v_fmac_f32_e32 v184, v72, v28
	v_fmac_f32_e32 v192, v80, v28
	v_fmac_f32_e32 v176, v65, v29
	v_fmac_f32_e32 v184, v73, v29
	v_fmac_f32_e32 v192, v81, v29
	v_fmac_f32_e32 v176, v66, v30
	v_fmac_f32_e32 v184, v74, v30
	v_fmac_f32_e32 v192, v82, v30
	v_fmac_f32_e32 v176, v67, v31
	v_fmac_f32_e32 v184, v75, v31
	v_fmac_f32_e32 v192, v83, v31
	ds_read_b128 v[24:27], v15 offset:512
	ds_read_b128 v[28:31], v15 offset:528
	s_waitcnt lgkmcnt(2)
	v_fmac_f32_e32 v177, v60, v16
	v_fmac_f32_e32 v185, v68, v16
	v_fmac_f32_e32 v193, v76, v16
	v_fmac_f32_e32 v177, v61, v17
	v_fmac_f32_e32 v185, v69, v17
	v_fmac_f32_e32 v193, v77, v17
	v_fmac_f32_e32 v177, v62, v18
	v_fmac_f32_e32 v185, v70, v18
	v_fmac_f32_e32 v193, v78, v18
	v_fmac_f32_e32 v177, v63, v19
	v_fmac_f32_e32 v185, v71, v19
	v_fmac_f32_e32 v193, v79, v19
	v_fmac_f32_e32 v177, v64, v20
	v_fmac_f32_e32 v185, v72, v20
	v_fmac_f32_e32 v193, v80, v20
	v_fmac_f32_e32 v177, v65, v21
	v_fmac_f32_e32 v185, v73, v21
	v_fmac_f32_e32 v193, v81, v21
	v_fmac_f32_e32 v177, v66, v22
	v_fmac_f32_e32 v185, v74, v22
	v_fmac_f32_e32 v193, v82, v22
	v_fmac_f32_e32 v177, v67, v23
	v_fmac_f32_e32 v185, v75, v23
	v_fmac_f32_e32 v193, v83, v23
	ds_read_b128 v[16:19], v15 offset:768
	ds_read_b128 v[20:23], v15 offset:784
	s_waitcnt lgkmcnt(2)
	v_fmac_f32_e32 v178, v60, v24
	v_fmac_f32_e32 v186, v68, v24
	v_fmac_f32_e32 v194, v76, v24
	v_fmac_f32_e32 v178, v61, v25
	v_fmac_f32_e32 v186, v69, v25
	v_fmac_f32_e32 v194, v77, v25
	v_fmac_f32_e32 v178, v62, v26
	v_fmac_f32_e32 v186, v70, v26
	v_fmac_f32_e32 v194, v78, v26
	v_fmac_f32_e32 v178, v63, v27
	v_fmac_f32_e32 v186, v71, v27
	v_fmac_f32_e32 v194, v79, v27
	v_fmac_f32_e32 v178, v64, v28
	v_fmac_f32_e32 v186, v72, v28
	v_fmac_f32_e32 v194, v80, v28
	v_fmac_f32_e32 v178, v65, v29
	v_fmac_f32_e32 v186, v73, v29
	v_fmac_f32_e32 v194, v81, v29
	v_fmac_f32_e32 v178, v66, v30
	v_fmac_f32_e32 v186, v74, v30
	v_fmac_f32_e32 v194, v82, v30
	v_fmac_f32_e32 v178, v67, v31
	v_fmac_f32_e32 v186, v75, v31
	v_fmac_f32_e32 v194, v83, v31
	ds_read_b128 v[24:27], v15 offset:1024
	ds_read_b128 v[28:31], v15 offset:1040
	s_waitcnt lgkmcnt(2)
	v_fmac_f32_e32 v179, v60, v16
	v_fmac_f32_e32 v187, v68, v16
	v_fmac_f32_e32 v195, v76, v16
	v_fmac_f32_e32 v179, v61, v17
	v_fmac_f32_e32 v187, v69, v17
	v_fmac_f32_e32 v195, v77, v17
	v_fmac_f32_e32 v179, v62, v18
	v_fmac_f32_e32 v187, v70, v18
	v_fmac_f32_e32 v195, v78, v18
	v_fmac_f32_e32 v179, v63, v19
	v_fmac_f32_e32 v187, v71, v19
	v_fmac_f32_e32 v195, v79, v19
	v_fmac_f32_e32 v179, v64, v20
	v_fmac_f32_e32 v187, v72, v20
	v_fmac_f32_e32 v195, v80, v20
	v_fmac_f32_e32 v179, v65, v21
	v_fmac_f32_e32 v187, v73, v21
	v_fmac_f32_e32 v195, v81, v21
	v_fmac_f32_e32 v179, v66, v22
	v_fmac_f32_e32 v187, v74, v22
	v_fmac_f32_e32 v195, v82, v22
	v_fmac_f32_e32 v179, v67, v23
	v_fmac_f32_e32 v187, v75, v23
	v_fmac_f32_e32 v195, v83, v23
	ds_read_b128 v[16:19], v15 offset:1280
	ds_read_b128 v[20:23], v15 offset:1296
	s_waitcnt lgkmcnt(2)
	v_fmac_f32_e32 v180, v60, v24
	v_fmac_f32_e32 v188, v68, v24
	v_fmac_f32_e32 v196, v76, v24
	v_fmac_f32_e32 v180, v61, v25
	v_fmac_f32_e32 v188, v69, v25
	v_fmac_f32_e32 v196, v77, v25
	v_fmac_f32_e32 v180, v62, v26
	v_fmac_f32_e32 v188, v70, v26
	v_fmac_f32_e32 v196, v78, v26
	v_fmac_f32_e32 v180, v63, v27
	v_fmac_f32_e32 v188, v71, v27
	v_fmac_f32_e32 v196, v79, v27
	v_fmac_f32_e32 v180, v64, v28
	v_fmac_f32_e32 v188, v72, v28
	v_fmac_f32_e32 v196, v80, v28
	v_fmac_f32_e32 v180, v65, v29
	v_fmac_f32_e32 v188, v73, v29
	v_fmac_f32_e32 v196, v81, v29
	v_fmac_f32_e32 v180, v66, v30
	v_fmac_f32_e32 v188, v74, v30
	v_fmac_f32_e32 v196, v82, v30
	v_fmac_f32_e32 v180, v67, v31
	v_fmac_f32_e32 v188, v75, v31
	v_fmac_f32_e32 v196, v83, v31
	ds_read_b128 v[24:27], v15 offset:1536
	ds_read_b128 v[28:31], v15 offset:1552
	s_waitcnt lgkmcnt(2)
	v_fmac_f32_e32 v181, v60, v16
	v_fmac_f32_e32 v189, v68, v16
	v_fmac_f32_e32 v197, v76, v16
	v_fmac_f32_e32 v181, v61, v17
	v_fmac_f32_e32 v189, v69, v17
	v_fmac_f32_e32 v197, v77, v17
	v_fmac_f32_e32 v181, v62, v18
	v_fmac_f32_e32 v189, v70, v18
	v_fmac_f32_e32 v197, v78, v18
	v_fmac_f32_e32 v181, v63, v19
	v_fmac_f32_e32 v189, v71, v19
	v_fmac_f32_e32 v197, v79, v19
	v_fmac_f32_e32 v181, v64, v20
	v_fmac_f32_e32 v189, v72, v20
	v_fmac_f32_e32 v197, v80, v20
	v_fmac_f32_e32 v181, v65, v21
	v_fmac_f32_e32 v189, v73, v21
	v_fmac_f32_e32 v197, v81, v21
	v_fmac_f32_e32 v181, v66, v22
	v_fmac_f32_e32 v189, v74, v22
	v_fmac_f32_e32 v197, v82, v22
	v_fmac_f32_e32 v181, v67, v23
	v_fmac_f32_e32 v189, v75, v23
	v_fmac_f32_e32 v197, v83, v23
	ds_read_b128 v[16:19], v15 offset:1792
	ds_read_b128 v[20:23], v15 offset:1808
	s_waitcnt lgkmcnt(2)
	v_fmac_f32_e32 v182, v60, v24
	v_fmac_f32_e32 v190, v68, v24
	v_fmac_f32_e32 v198, v76, v24
	v_fmac_f32_e32 v182, v61, v25
	v_fmac_f32_e32 v190, v69, v25
	v_fmac_f32_e32 v198, v77, v25
	v_fmac_f32_e32 v182, v62, v26
	v_fmac_f32_e32 v190, v70, v26
	v_fmac_f32_e32 v198, v78, v26
	v_fmac_f32_e32 v182, v63, v27
	v_fmac_f32_e32 v190, v71, v27
	v_fmac_f32_e32 v198, v79, v27
	v_fmac_f32_e32 v182, v64, v28
	v_fmac_f32_e32 v190, v72, v28
	v_fmac_f32_e32 v198, v80, v28
	v_fmac_f32_e32 v182, v65, v29
	v_fmac_f32_e32 v190, v73, v29
	v_fmac_f32_e32 v198, v81, v29
	v_fmac_f32_e32 v182, v66, v30
	v_fmac_f32_e32 v190, v74, v30
	v_fmac_f32_e32 v198, v82, v30
	v_fmac_f32_e32 v182, v67, v31
	v_fmac_f32_e32 v190, v75, v31
	v_fmac_f32_e32 v198, v83, v31
	ds_read_b128 v[24:27], v15 offset:32
	ds_read_b128 v[28:31], v15 offset:48
	s_waitcnt lgkmcnt(2)
	v_fmac_f32_e32 v183, v60, v16
	v_fmac_f32_e32 v191, v68, v16
	v_fmac_f32_e32 v199, v76, v16
	v_fmac_f32_e32 v183, v61, v17
	v_fmac_f32_e32 v191, v69, v17
	v_fmac_f32_e32 v199, v77, v17
	v_fmac_f32_e32 v183, v62, v18
	v_fmac_f32_e32 v191, v70, v18
	v_fmac_f32_e32 v199, v78, v18
	v_fmac_f32_e32 v183, v63, v19
	v_fmac_f32_e32 v191, v71, v19
	v_fmac_f32_e32 v199, v79, v19
	v_fmac_f32_e32 v183, v64, v20
	v_fmac_f32_e32 v191, v72, v20
	v_fmac_f32_e32 v199, v80, v20
	v_fmac_f32_e32 v183, v65, v21
	v_fmac_f32_e32 v191, v73, v21
	v_fmac_f32_e32 v199, v81, v21
	v_fmac_f32_e32 v183, v66, v22
	v_fmac_f32_e32 v191, v74, v22
	v_fmac_f32_e32 v199, v82, v22
	v_fmac_f32_e32 v183, v67, v23
	v_fmac_f32_e32 v191, v75, v23
	v_fmac_f32_e32 v199, v83, v23
	ds_read_b128 v[60:63], v32 offset:64
	ds_read_b128 v[64:67], v32 offset:80
	ds_read_b128 v[68:71], v33 offset:64
	ds_read_b128 v[72:75], v33 offset:80
	ds_read_b128 v[76:79], v34 offset:64
	ds_read_b128 v[80:83], v34 offset:80
	ds_read_b128 v[16:19], v15 offset:288
	ds_read_b128 v[20:23], v15 offset:304
	s_waitcnt lgkmcnt(8)
	v_fmac_f32_e32 v176, v84, v24
	v_fmac_f32_e32 v184, v92, v24
	v_fmac_f32_e32 v192, v100, v24
	v_fmac_f32_e32 v176, v85, v25
	v_fmac_f32_e32 v184, v93, v25
	v_fmac_f32_e32 v192, v101, v25
	v_fmac_f32_e32 v176, v86, v26
	v_fmac_f32_e32 v184, v94, v26
	v_fmac_f32_e32 v192, v102, v26
	v_fmac_f32_e32 v176, v87, v27
	v_fmac_f32_e32 v184, v95, v27
	v_fmac_f32_e32 v192, v103, v27
	v_fmac_f32_e32 v176, v88, v28
	v_fmac_f32_e32 v184, v96, v28
	v_fmac_f32_e32 v192, v104, v28
	v_fmac_f32_e32 v176, v89, v29
	v_fmac_f32_e32 v184, v97, v29
	v_fmac_f32_e32 v192, v105, v29
	v_fmac_f32_e32 v176, v90, v30
	v_fmac_f32_e32 v184, v98, v30
	v_fmac_f32_e32 v192, v106, v30
	v_fmac_f32_e32 v176, v91, v31
	v_fmac_f32_e32 v184, v99, v31
	v_fmac_f32_e32 v192, v107, v31
	ds_read_b128 v[24:27], v15 offset:544
	ds_read_b128 v[28:31], v15 offset:560
	s_waitcnt lgkmcnt(2)
	v_fmac_f32_e32 v177, v84, v16
	v_fmac_f32_e32 v185, v92, v16
	v_fmac_f32_e32 v193, v100, v16
	v_fmac_f32_e32 v177, v85, v17
	v_fmac_f32_e32 v185, v93, v17
	v_fmac_f32_e32 v193, v101, v17
	v_fmac_f32_e32 v177, v86, v18
	v_fmac_f32_e32 v185, v94, v18
	v_fmac_f32_e32 v193, v102, v18
	v_fmac_f32_e32 v177, v87, v19
	v_fmac_f32_e32 v185, v95, v19
	v_fmac_f32_e32 v193, v103, v19
	v_fmac_f32_e32 v177, v88, v20
	v_fmac_f32_e32 v185, v96, v20
	v_fmac_f32_e32 v193, v104, v20
	v_fmac_f32_e32 v177, v89, v21
	v_fmac_f32_e32 v185, v97, v21
	v_fmac_f32_e32 v193, v105, v21
	v_fmac_f32_e32 v177, v90, v22
	v_fmac_f32_e32 v185, v98, v22
	v_fmac_f32_e32 v193, v106, v22
	v_fmac_f32_e32 v177, v91, v23
	v_fmac_f32_e32 v185, v99, v23
	v_fmac_f32_e32 v193, v107, v23
	ds_read_b128 v[16:19], v15 offset:800
	ds_read_b128 v[20:23], v15 offset:816
	s_waitcnt lgkmcnt(2)
	v_fmac_f32_e32 v178, v84, v24
	v_fmac_f32_e32 v186, v92, v24
	v_fmac_f32_e32 v194, v100, v24
	v_fmac_f32_e32 v178, v85, v25
	v_fmac_f32_e32 v186, v93, v25
	v_fmac_f32_e32 v194, v101, v25
	v_fmac_f32_e32 v178, v86, v26
	v_fmac_f32_e32 v186, v94, v26
	v_fmac_f32_e32 v194, v102, v26
	v_fmac_f32_e32 v178, v87, v27
	v_fmac_f32_e32 v186, v95, v27
	v_fmac_f32_e32 v194, v103, v27
	v_fmac_f32_e32 v178, v88, v28
	v_fmac_f32_e32 v186, v96, v28
	v_fmac_f32_e32 v194, v104, v28
	v_fmac_f32_e32 v178, v89, v29
	v_fmac_f32_e32 v186, v97, v29
	v_fmac_f32_e32 v194, v105, v29
	v_fmac_f32_e32 v178, v90, v30
	v_fmac_f32_e32 v186, v98, v30
	v_fmac_f32_e32 v194, v106, v30
	v_fmac_f32_e32 v178, v91, v31
	v_fmac_f32_e32 v186, v99, v31
	v_fmac_f32_e32 v194, v107, v31
	ds_read_b128 v[24:27], v15 offset:1056
	ds_read_b128 v[28:31], v15 offset:1072
	s_waitcnt lgkmcnt(2)
	v_fmac_f32_e32 v179, v84, v16
	v_fmac_f32_e32 v187, v92, v16
	v_fmac_f32_e32 v195, v100, v16
	v_fmac_f32_e32 v179, v85, v17
	v_fmac_f32_e32 v187, v93, v17
	v_fmac_f32_e32 v195, v101, v17
	v_fmac_f32_e32 v179, v86, v18
	v_fmac_f32_e32 v187, v94, v18
	v_fmac_f32_e32 v195, v102, v18
	v_fmac_f32_e32 v179, v87, v19
	v_fmac_f32_e32 v187, v95, v19
	v_fmac_f32_e32 v195, v103, v19
	v_fmac_f32_e32 v179, v88, v20
	v_fmac_f32_e32 v187, v96, v20
	v_fmac_f32_e32 v195, v104, v20
	v_fmac_f32_e32 v179, v89, v21
	v_fmac_f32_e32 v187, v97, v21
	v_fmac_f32_e32 v195, v105, v21
	v_fmac_f32_e32 v179, v90, v22
	v_fmac_f32_e32 v187, v98, v22
	v_fmac_f32_e32 v195, v106, v22
	v_fmac_f32_e32 v179, v91, v23
	v_fmac_f32_e32 v187, v99, v23
	v_fmac_f32_e32 v195, v107, v23
	ds_read_b128 v[16:19], v15 offset:1312
	ds_read_b128 v[20:23], v15 offset:1328
	s_waitcnt lgkmcnt(2)
	v_fmac_f32_e32 v180, v84, v24
	v_fmac_f32_e32 v188, v92, v24
	v_fmac_f32_e32 v196, v100, v24
	v_fmac_f32_e32 v180, v85, v25
	v_fmac_f32_e32 v188, v93, v25
	v_fmac_f32_e32 v196, v101, v25
	v_fmac_f32_e32 v180, v86, v26
	v_fmac_f32_e32 v188, v94, v26
	v_fmac_f32_e32 v196, v102, v26
	v_fmac_f32_e32 v180, v87, v27
	v_fmac_f32_e32 v188, v95, v27
	v_fmac_f32_e32 v196, v103, v27
	v_fmac_f32_e32 v180, v88, v28
	v_fmac_f32_e32 v188, v96, v28
	v_fmac_f32_e32 v196, v104, v28
	v_fmac_f32_e32 v180, v89, v29
	v_fmac_f32_e32 v188, v97, v29
	v_fmac_f32_e32 v196, v105, v29
	v_fmac_f32_e32 v180, v90, v30
	v_fmac_f32_e32 v188, v98, v30
	v_fmac_f32_e32 v196, v106, v30
	v_fmac_f32_e32 v180, v91, v31
	v_fmac_f32_e32 v188, v99, v31
	v_fmac_f32_e32 v196, v107, v31
	ds_read_b128 v[24:27], v15 offset:1568
	ds_read_b128 v[28:31], v15 offset:1584
	s_waitcnt lgkmcnt(2)
	v_fmac_f32_e32 v181, v84, v16
	v_fmac_f32_e32 v189, v92, v16
	v_fmac_f32_e32 v197, v100, v16
	v_fmac_f32_e32 v181, v85, v17
	v_fmac_f32_e32 v189, v93, v17
	v_fmac_f32_e32 v197, v101, v17
	v_fmac_f32_e32 v181, v86, v18
	v_fmac_f32_e32 v189, v94, v18
	v_fmac_f32_e32 v197, v102, v18
	v_fmac_f32_e32 v181, v87, v19
	v_fmac_f32_e32 v189, v95, v19
	v_fmac_f32_e32 v197, v103, v19
	v_fmac_f32_e32 v181, v88, v20
	v_fmac_f32_e32 v189, v96, v20
	v_fmac_f32_e32 v197, v104, v20
	v_fmac_f32_e32 v181, v89, v21
	v_fmac_f32_e32 v189, v97, v21
	v_fmac_f32_e32 v197, v105, v21
	v_fmac_f32_e32 v181, v90, v22
	v_fmac_f32_e32 v189, v98, v22
	v_fmac_f32_e32 v197, v106, v22
	v_fmac_f32_e32 v181, v91, v23
	v_fmac_f32_e32 v189, v99, v23
	v_fmac_f32_e32 v197, v107, v23
	ds_read_b128 v[16:19], v15 offset:1824
	ds_read_b128 v[20:23], v15 offset:1840
	s_waitcnt lgkmcnt(2)
	v_fmac_f32_e32 v182, v84, v24
	v_fmac_f32_e32 v190, v92, v24
	v_fmac_f32_e32 v198, v100, v24
	v_fmac_f32_e32 v182, v85, v25
	v_fmac_f32_e32 v190, v93, v25
	v_fmac_f32_e32 v198, v101, v25
	v_fmac_f32_e32 v182, v86, v26
	v_fmac_f32_e32 v190, v94, v26
	v_fmac_f32_e32 v198, v102, v26
	v_fmac_f32_e32 v182, v87, v27
	v_fmac_f32_e32 v190, v95, v27
	v_fmac_f32_e32 v198, v103, v27
	v_fmac_f32_e32 v182, v88, v28
	v_fmac_f32_e32 v190, v96, v28
	v_fmac_f32_e32 v198, v104, v28
	v_fmac_f32_e32 v182, v89, v29
	v_fmac_f32_e32 v190, v97, v29
	v_fmac_f32_e32 v198, v105, v29
	v_fmac_f32_e32 v182, v90, v30
	v_fmac_f32_e32 v190, v98, v30
	v_fmac_f32_e32 v198, v106, v30
	v_fmac_f32_e32 v182, v91, v31
	v_fmac_f32_e32 v190, v99, v31
	v_fmac_f32_e32 v198, v107, v31
	ds_read_b128 v[24:27], v15 offset:64
	ds_read_b128 v[28:31], v15 offset:80
	s_waitcnt lgkmcnt(2)
	v_fmac_f32_e32 v183, v84, v16
	v_fmac_f32_e32 v191, v92, v16
	v_fmac_f32_e32 v199, v100, v16
	v_fmac_f32_e32 v183, v85, v17
	v_fmac_f32_e32 v191, v93, v17
	v_fmac_f32_e32 v199, v101, v17
	v_fmac_f32_e32 v183, v86, v18
	v_fmac_f32_e32 v191, v94, v18
	v_fmac_f32_e32 v199, v102, v18
	v_fmac_f32_e32 v183, v87, v19
	v_fmac_f32_e32 v191, v95, v19
	v_fmac_f32_e32 v199, v103, v19
	v_fmac_f32_e32 v183, v88, v20
	v_fmac_f32_e32 v191, v96, v20
	v_fmac_f32_e32 v199, v104, v20
	v_fmac_f32_e32 v183, v89, v21
	v_fmac_f32_e32 v191, v97, v21
	v_fmac_f32_e32 v199, v105, v21
	v_fmac_f32_e32 v183, v90, v22
	v_fmac_f32_e32 v191, v98, v22
	v_fmac_f32_e32 v199, v106, v22
	v_fmac_f32_e32 v183, v91, v23
	v_fmac_f32_e32 v191, v99, v23
	v_fmac_f32_e32 v199, v107, v23
	v_add_u32_e32 v32, 64, v32
	v_add_u32_e32 v33, 64, v33
	v_add_u32_e32 v34, 64, v34
	v_add_u32_e32 v15, 64, v15
	s_add_i32 s17, s17, 1
	s_cmp_lt_u32 s17, 4
	s_cbranch_scc1 .Lsm_qk
	s_waitcnt lgkmcnt(0)
	v_sub_u32_e32 v10, s3, v108
	v_add_u32_e32 v38, 0, v10
	v_cvt_f32_i32_e32 v39, v38
	v_cmp_gt_u32_e32 vcc, s3, v38
	v_mul_f32_e32 v39, v14, v39
	v_fma_f32 v176, v176, s52, -v39
	v_cndmask_b32_e32 v176, v241, v176, vcc
	v_add_u32_e32 v38, 0xffffffc0, v10
	v_cvt_f32_i32_e32 v39, v38
	v_cmp_gt_u32_e32 vcc, s3, v38
	v_mul_f32_e32 v39, v14, v39
	v_fma_f32 v184, v184, s52, -v39
	v_cndmask_b32_e32 v184, v241, v184, vcc
	v_add_u32_e32 v38, 0xffffff80, v10
	v_cvt_f32_i32_e32 v39, v38
	v_cmp_gt_u32_e32 vcc, s3, v38
	v_mul_f32_e32 v39, v14, v39
	v_fma_f32 v192, v192, s52, -v39
	s_and_b64 vcc, s[40:41], vcc
	v_cndmask_b32_e32 v192, v241, v192, vcc
	v_add_u32_e32 v38, 1, v10
	v_cvt_f32_i32_e32 v39, v38
	v_cmp_gt_u32_e32 vcc, s3, v38
	v_mul_f32_e32 v39, v14, v39
	v_fma_f32 v177, v177, s52, -v39
	v_cndmask_b32_e32 v177, v241, v177, vcc
	v_add_u32_e32 v38, 0xffffffc1, v10
	v_cvt_f32_i32_e32 v39, v38
	v_cmp_gt_u32_e32 vcc, s3, v38
	v_mul_f32_e32 v39, v14, v39
	v_fma_f32 v185, v185, s52, -v39
	v_cndmask_b32_e32 v185, v241, v185, vcc
	v_add_u32_e32 v38, 0xffffff81, v10
	v_cvt_f32_i32_e32 v39, v38
	v_cmp_gt_u32_e32 vcc, s3, v38
	v_mul_f32_e32 v39, v14, v39
	v_fma_f32 v193, v193, s52, -v39
	s_and_b64 vcc, s[40:41], vcc
	v_cndmask_b32_e32 v193, v241, v193, vcc
	v_add_u32_e32 v38, 2, v10
	v_cvt_f32_i32_e32 v39, v38
	v_cmp_gt_u32_e32 vcc, s3, v38
	v_mul_f32_e32 v39, v14, v39
	v_fma_f32 v178, v178, s52, -v39
	v_cndmask_b32_e32 v178, v241, v178, vcc
	v_add_u32_e32 v38, 0xffffffc2, v10
	v_cvt_f32_i32_e32 v39, v38
	v_cmp_gt_u32_e32 vcc, s3, v38
	v_mul_f32_e32 v39, v14, v39
	v_fma_f32 v186, v186, s52, -v39
	v_cndmask_b32_e32 v186, v241, v186, vcc
	v_add_u32_e32 v38, 0xffffff82, v10
	v_cvt_f32_i32_e32 v39, v38
	v_cmp_gt_u32_e32 vcc, s3, v38
	v_mul_f32_e32 v39, v14, v39
	v_fma_f32 v194, v194, s52, -v39
	s_and_b64 vcc, s[40:41], vcc
	v_cndmask_b32_e32 v194, v241, v194, vcc
	v_add_u32_e32 v38, 3, v10
	v_cvt_f32_i32_e32 v39, v38
	v_cmp_gt_u32_e32 vcc, s3, v38
	v_mul_f32_e32 v39, v14, v39
	v_fma_f32 v179, v179, s52, -v39
	v_cndmask_b32_e32 v179, v241, v179, vcc
	v_add_u32_e32 v38, 0xffffffc3, v10
	v_cvt_f32_i32_e32 v39, v38
	v_cmp_gt_u32_e32 vcc, s3, v38
	v_mul_f32_e32 v39, v14, v39
	v_fma_f32 v187, v187, s52, -v39
	v_cndmask_b32_e32 v187, v241, v187, vcc
	v_add_u32_e32 v38, 0xffffff83, v10
	v_cvt_f32_i32_e32 v39, v38
	v_cmp_gt_u32_e32 vcc, s3, v38
	v_mul_f32_e32 v39, v14, v39
	v_fma_f32 v195, v195, s52, -v39
	s_and_b64 vcc, s[40:41], vcc
	v_cndmask_b32_e32 v195, v241, v195, vcc
	v_add_u32_e32 v38, 4, v10
	v_cvt_f32_i32_e32 v39, v38
	v_cmp_gt_u32_e32 vcc, s3, v38
	v_mul_f32_e32 v39, v14, v39
	v_fma_f32 v180, v180, s52, -v39
	v_cndmask_b32_e32 v180, v241, v180, vcc
	v_add_u32_e32 v38, 0xffffffc4, v10
	v_cvt_f32_i32_e32 v39, v38
	v_cmp_gt_u32_e32 vcc, s3, v38
	v_mul_f32_e32 v39, v14, v39
	v_fma_f32 v188, v188, s52, -v39
	v_cndmask_b32_e32 v188, v241, v188, vcc
	v_add_u32_e32 v38, 0xffffff84, v10
	v_cvt_f32_i32_e32 v39, v38
	v_cmp_gt_u32_e32 vcc, s3, v38
	v_mul_f32_e32 v39, v14, v39
	v_fma_f32 v196, v196, s52, -v39
	s_and_b64 vcc, s[40:41], vcc
	v_cndmask_b32_e32 v196, v241, v196, vcc
	v_add_u32_e32 v38, 5, v10
	v_cvt_f32_i32_e32 v39, v38
	v_cmp_gt_u32_e32 vcc, s3, v38
	v_mul_f32_e32 v39, v14, v39
	v_fma_f32 v181, v181, s52, -v39
	v_cndmask_b32_e32 v181, v241, v181, vcc
	v_add_u32_e32 v38, 0xffffffc5, v10
	v_cvt_f32_i32_e32 v39, v38
	v_cmp_gt_u32_e32 vcc, s3, v38
	v_mul_f32_e32 v39, v14, v39
	v_fma_f32 v189, v189, s52, -v39
	v_cndmask_b32_e32 v189, v241, v189, vcc
	v_add_u32_e32 v38, 0xffffff85, v10
	v_cvt_f32_i32_e32 v39, v38
	v_cmp_gt_u32_e32 vcc, s3, v38
	v_mul_f32_e32 v39, v14, v39
	v_fma_f32 v197, v197, s52, -v39
	s_and_b64 vcc, s[40:41], vcc
	v_cndmask_b32_e32 v197, v241, v197, vcc
	v_add_u32_e32 v38, 6, v10
	v_cvt_f32_i32_e32 v39, v38
	v_cmp_gt_u32_e32 vcc, s3, v38
	v_mul_f32_e32 v39, v14, v39
	v_fma_f32 v182, v182, s52, -v39
	v_cndmask_b32_e32 v182, v241, v182, vcc
	v_add_u32_e32 v38, 0xffffffc6, v10
	v_cvt_f32_i32_e32 v39, v38
	v_cmp_gt_u32_e32 vcc, s3, v38
	v_mul_f32_e32 v39, v14, v39
	v_fma_f32 v190, v190, s52, -v39
	v_cndmask_b32_e32 v190, v241, v190, vcc
	v_add_u32_e32 v38, 0xffffff86, v10
	v_cvt_f32_i32_e32 v39, v38
	v_cmp_gt_u32_e32 vcc, s3, v38
	v_mul_f32_e32 v39, v14, v39
	v_fma_f32 v198, v198, s52, -v39
	s_and_b64 vcc, s[40:41], vcc
	v_cndmask_b32_e32 v198, v241, v198, vcc
	v_add_u32_e32 v38, 7, v10
	v_cvt_f32_i32_e32 v39, v38
	v_cmp_gt_u32_e32 vcc, s3, v38
	v_mul_f32_e32 v39, v14, v39
	v_fma_f32 v183, v183, s52, -v39
	v_cndmask_b32_e32 v183, v241, v183, vcc
	v_add_u32_e32 v38, 0xffffffc7, v10
	v_cvt_f32_i32_e32 v39, v38
	v_cmp_gt_u32_e32 vcc, s3, v38
	v_mul_f32_e32 v39, v14, v39
	v_fma_f32 v191, v191, s52, -v39
	v_cndmask_b32_e32 v191, v241, v191, vcc
	v_add_u32_e32 v38, 0xffffff87, v10
	v_cvt_f32_i32_e32 v39, v38
	v_cmp_gt_u32_e32 vcc, s3, v38
	v_mul_f32_e32 v39, v14, v39
	v_fma_f32 v199, v199, s52, -v39
	s_and_b64 vcc, s[40:41], vcc
	v_cndmask_b32_e32 v199, v241, v199, vcc
	v_max3_f32 v216, v176, v184, v192
	v_max3_f32 v217, v177, v185, v193
	v_max3_f32 v218, v178, v186, v194
	v_max3_f32 v219, v179, v187, v195
	v_max3_f32 v220, v180, v188, v196
	v_max3_f32 v221, v181, v189, v197
	v_max3_f32 v222, v182, v190, v198
	v_max3_f32 v223, v183, v191, v199
	v_max_f32_dpp v216, v216, v216 quad_perm:[1,0,3,2] row_mask:0xf bank_mask:0xf
	v_max_f32_dpp v217, v217, v217 quad_perm:[1,0,3,2] row_mask:0xf bank_mask:0xf
	v_max_f32_dpp v218, v218, v218 quad_perm:[1,0,3,2] row_mask:0xf bank_mask:0xf
	v_max_f32_dpp v219, v219, v219 quad_perm:[1,0,3,2] row_mask:0xf bank_mask:0xf
	v_max_f32_dpp v220, v220, v220 quad_perm:[1,0,3,2] row_mask:0xf bank_mask:0xf
	v_max_f32_dpp v221, v221, v221 quad_perm:[1,0,3,2] row_mask:0xf bank_mask:0xf
	v_max_f32_dpp v222, v222, v222 quad_perm:[1,0,3,2] row_mask:0xf bank_mask:0xf
	v_max_f32_dpp v223, v223, v223 quad_perm:[1,0,3,2] row_mask:0xf bank_mask:0xf
	v_max_f32_dpp v216, v216, v216 quad_perm:[2,3,0,1] row_mask:0xf bank_mask:0xf
	v_max_f32_dpp v217, v217, v217 quad_perm:[2,3,0,1] row_mask:0xf bank_mask:0xf
	v_max_f32_dpp v218, v218, v218 quad_perm:[2,3,0,1] row_mask:0xf bank_mask:0xf
	v_max_f32_dpp v219, v219, v219 quad_perm:[2,3,0,1] row_mask:0xf bank_mask:0xf
	v_max_f32_dpp v220, v220, v220 quad_perm:[2,3,0,1] row_mask:0xf bank_mask:0xf
	v_max_f32_dpp v221, v221, v221 quad_perm:[2,3,0,1] row_mask:0xf bank_mask:0xf
	v_max_f32_dpp v222, v222, v222 quad_perm:[2,3,0,1] row_mask:0xf bank_mask:0xf
	v_max_f32_dpp v223, v223, v223 quad_perm:[2,3,0,1] row_mask:0xf bank_mask:0xf
	v_max_f32_dpp v216, v216, v216 row_half_mirror row_mask:0xf bank_mask:0xf
	v_max_f32_dpp v217, v217, v217 row_half_mirror row_mask:0xf bank_mask:0xf
	v_max_f32_dpp v218, v218, v218 row_half_mirror row_mask:0xf bank_mask:0xf
	v_max_f32_dpp v219, v219, v219 row_half_mirror row_mask:0xf bank_mask:0xf
	v_max_f32_dpp v220, v220, v220 row_half_mirror row_mask:0xf bank_mask:0xf
	v_max_f32_dpp v221, v221, v221 row_half_mirror row_mask:0xf bank_mask:0xf
	v_max_f32_dpp v222, v222, v222 row_half_mirror row_mask:0xf bank_mask:0xf
	v_max_f32_dpp v223, v223, v223 row_half_mirror row_mask:0xf bank_mask:0xf
	v_max_f32_dpp v216, v216, v216 row_mirror row_mask:0xf bank_mask:0xf
	v_max_f32_dpp v217, v217, v217 row_mirror row_mask:0xf bank_mask:0xf
	v_max_f32_dpp v218, v218, v218 row_mirror row_mask:0xf bank_mask:0xf
	v_max_f32_dpp v219, v219, v219 row_mirror row_mask:0xf bank_mask:0xf
	v_max_f32_dpp v220, v220, v220 row_mirror row_mask:0xf bank_mask:0xf
	v_max_f32_dpp v221, v221, v221 row_mirror row_mask:0xf bank_mask:0xf
	v_max_f32_dpp v222, v222, v222 row_mirror row_mask:0xf bank_mask:0xf
	v_max_f32_dpp v223, v223, v223 row_mirror row_mask:0xf bank_mask:0xf
	v_max_f32_dpp v216, v216, v216 row_bcast:15 row_mask:0xa bank_mask:0xf
	v_max_f32_dpp v217, v217, v217 row_bcast:15 row_mask:0xa bank_mask:0xf
	v_max_f32_dpp v218, v218, v218 row_bcast:15 row_mask:0xa bank_mask:0xf
	v_max_f32_dpp v219, v219, v219 row_bcast:15 row_mask:0xa bank_mask:0xf
	v_max_f32_dpp v220, v220, v220 row_bcast:15 row_mask:0xa bank_mask:0xf
	v_max_f32_dpp v221, v221, v221 row_bcast:15 row_mask:0xa bank_mask:0xf
	v_max_f32_dpp v222, v222, v222 row_bcast:15 row_mask:0xa bank_mask:0xf
	v_max_f32_dpp v223, v223, v223 row_bcast:15 row_mask:0xa bank_mask:0xf
	v_max_f32_dpp v216, v216, v216 row_bcast:31 row_mask:0xc bank_mask:0xf
	v_max_f32_dpp v217, v217, v217 row_bcast:31 row_mask:0xc bank_mask:0xf
	v_max_f32_dpp v218, v218, v218 row_bcast:31 row_mask:0xc bank_mask:0xf
	v_max_f32_dpp v219, v219, v219 row_bcast:31 row_mask:0xc bank_mask:0xf
	v_max_f32_dpp v220, v220, v220 row_bcast:31 row_mask:0xc bank_mask:0xf
	v_max_f32_dpp v221, v221, v221 row_bcast:31 row_mask:0xc bank_mask:0xf
	v_max_f32_dpp v222, v222, v222 row_bcast:31 row_mask:0xc bank_mask:0xf
	v_max_f32_dpp v223, v223, v223 row_bcast:31 row_mask:0xc bank_mask:0xf
	v_readlane_b32 s4, v216, 63
	v_readlane_b32 s5, v217, 63
	v_readlane_b32 s26, v218, 63
	v_readlane_b32 s27, v219, 63
	v_readlane_b32 s44, v220, 63
	v_readlane_b32 s45, v221, 63
	v_readlane_b32 s46, v222, 63
	v_readlane_b32 s47, v223, 63
	v_max_f32_e32 v216, s4, v59
	v_max_f32_e32 v217, s5, v59
	v_max_f32_e32 v218, s26, v59
	v_max_f32_e32 v219, s27, v59
	v_max_f32_e32 v220, s44, v59
	v_max_f32_e32 v221, s45, v59
	v_max_f32_e32 v222, s46, v59
	v_max_f32_e32 v223, s47, v59
	v_sub_f32_e32 v176, v176, v216
	v_mul_f32_e32 v176, 0x3fb8aa3b, v176
	v_sub_f32_e32 v184, v184, v216
	v_mul_f32_e32 v184, 0x3fb8aa3b, v184
	v_sub_f32_e32 v192, v192, v216
	v_mul_f32_e32 v192, 0x3fb8aa3b, v192
	v_exp_f32_e32 v176, v176
	v_exp_f32_e32 v184, v184
	v_exp_f32_e32 v192, v192
	v_add_f32_e32 v224, v176, v184
	v_sub_f32_e32 v232, v59, v216
	v_add_f32_e32 v224, v224, v192
	v_mul_f32_e32 v232, 0x3fb8aa3b, v232
	v_exp_f32_e32 v232, v232
	v_sub_f32_e32 v177, v177, v217
	v_mul_f32_e32 v177, 0x3fb8aa3b, v177
	v_sub_f32_e32 v185, v185, v217
	v_mul_f32_e32 v185, 0x3fb8aa3b, v185
	v_sub_f32_e32 v193, v193, v217
	v_mul_f32_e32 v193, 0x3fb8aa3b, v193
	v_exp_f32_e32 v177, v177
	v_exp_f32_e32 v185, v185
	v_exp_f32_e32 v193, v193
	v_add_f32_e32 v225, v177, v185
	v_sub_f32_e32 v233, v59, v217
	v_add_f32_e32 v225, v225, v193
	v_mul_f32_e32 v233, 0x3fb8aa3b, v233
	v_exp_f32_e32 v233, v233
	v_sub_f32_e32 v178, v178, v218
	v_mul_f32_e32 v178, 0x3fb8aa3b, v178
	v_sub_f32_e32 v186, v186, v218
	v_mul_f32_e32 v186, 0x3fb8aa3b, v186
	v_sub_f32_e32 v194, v194, v218
	v_mul_f32_e32 v194, 0x3fb8aa3b, v194
	v_exp_f32_e32 v178, v178
	v_exp_f32_e32 v186, v186
	v_exp_f32_e32 v194, v194
	v_add_f32_e32 v226, v178, v186
	v_sub_f32_e32 v234, v59, v218
	v_add_f32_e32 v226, v226, v194
	v_mul_f32_e32 v234, 0x3fb8aa3b, v234
	v_exp_f32_e32 v234, v234
	v_sub_f32_e32 v179, v179, v219
	v_mul_f32_e32 v179, 0x3fb8aa3b, v179
	v_sub_f32_e32 v187, v187, v219
	v_mul_f32_e32 v187, 0x3fb8aa3b, v187
	v_sub_f32_e32 v195, v195, v219
	v_mul_f32_e32 v195, 0x3fb8aa3b, v195
	v_exp_f32_e32 v179, v179
	v_exp_f32_e32 v187, v187
	v_exp_f32_e32 v195, v195
	v_add_f32_e32 v227, v179, v187
	v_sub_f32_e32 v235, v59, v219
	v_add_f32_e32 v227, v227, v195
	v_mul_f32_e32 v235, 0x3fb8aa3b, v235
	v_exp_f32_e32 v235, v235
	v_sub_f32_e32 v180, v180, v220
	v_mul_f32_e32 v180, 0x3fb8aa3b, v180
	v_sub_f32_e32 v188, v188, v220
	v_mul_f32_e32 v188, 0x3fb8aa3b, v188
	v_sub_f32_e32 v196, v196, v220
	v_mul_f32_e32 v196, 0x3fb8aa3b, v196
	v_exp_f32_e32 v180, v180
	v_exp_f32_e32 v188, v188
	v_exp_f32_e32 v196, v196
	v_add_f32_e32 v228, v180, v188
	v_sub_f32_e32 v236, v59, v220
	v_add_f32_e32 v228, v228, v196
	v_mul_f32_e32 v236, 0x3fb8aa3b, v236
	v_exp_f32_e32 v236, v236
	v_sub_f32_e32 v181, v181, v221
	v_mul_f32_e32 v181, 0x3fb8aa3b, v181
	v_sub_f32_e32 v189, v189, v221
	v_mul_f32_e32 v189, 0x3fb8aa3b, v189
	v_sub_f32_e32 v197, v197, v221
	v_mul_f32_e32 v197, 0x3fb8aa3b, v197
	v_exp_f32_e32 v181, v181
	v_exp_f32_e32 v189, v189
	v_exp_f32_e32 v197, v197
	v_add_f32_e32 v229, v181, v189
	v_sub_f32_e32 v237, v59, v221
	v_add_f32_e32 v229, v229, v197
	v_mul_f32_e32 v237, 0x3fb8aa3b, v237
	v_exp_f32_e32 v237, v237
	v_sub_f32_e32 v182, v182, v222
	v_mul_f32_e32 v182, 0x3fb8aa3b, v182
	v_sub_f32_e32 v190, v190, v222
	v_mul_f32_e32 v190, 0x3fb8aa3b, v190
	v_sub_f32_e32 v198, v198, v222
	v_mul_f32_e32 v198, 0x3fb8aa3b, v198
	v_exp_f32_e32 v182, v182
	v_exp_f32_e32 v190, v190
	v_exp_f32_e32 v198, v198
	v_add_f32_e32 v230, v182, v190
	v_sub_f32_e32 v238, v59, v222
	v_add_f32_e32 v230, v230, v198
	v_mul_f32_e32 v238, 0x3fb8aa3b, v238
	v_exp_f32_e32 v238, v238
	v_sub_f32_e32 v183, v183, v223
	v_mul_f32_e32 v183, 0x3fb8aa3b, v183
	v_sub_f32_e32 v191, v191, v223
	v_mul_f32_e32 v191, 0x3fb8aa3b, v191
	v_sub_f32_e32 v199, v199, v223
	v_mul_f32_e32 v199, 0x3fb8aa3b, v199
	v_exp_f32_e32 v183, v183
	v_exp_f32_e32 v191, v191
	v_exp_f32_e32 v199, v199
	v_add_f32_e32 v231, v183, v191
	v_sub_f32_e32 v239, v59, v223
	v_add_f32_e32 v231, v231, v199
	v_mul_f32_e32 v239, 0x3fb8aa3b, v239
	v_exp_f32_e32 v239, v239
	v_add_f32_dpp v224, v224, v224 quad_perm:[1,0,3,2] row_mask:0xf bank_mask:0xf bound_ctrl:1
	v_add_f32_dpp v225, v225, v225 quad_perm:[1,0,3,2] row_mask:0xf bank_mask:0xf bound_ctrl:1
	v_add_f32_dpp v226, v226, v226 quad_perm:[1,0,3,2] row_mask:0xf bank_mask:0xf bound_ctrl:1
	v_add_f32_dpp v227, v227, v227 quad_perm:[1,0,3,2] row_mask:0xf bank_mask:0xf bound_ctrl:1
	v_add_f32_dpp v228, v228, v228 quad_perm:[1,0,3,2] row_mask:0xf bank_mask:0xf bound_ctrl:1
	v_add_f32_dpp v229, v229, v229 quad_perm:[1,0,3,2] row_mask:0xf bank_mask:0xf bound_ctrl:1
	v_add_f32_dpp v230, v230, v230 quad_perm:[1,0,3,2] row_mask:0xf bank_mask:0xf bound_ctrl:1
	v_add_f32_dpp v231, v231, v231 quad_perm:[1,0,3,2] row_mask:0xf bank_mask:0xf bound_ctrl:1
	v_add_f32_dpp v224, v224, v224 quad_perm:[2,3,0,1] row_mask:0xf bank_mask:0xf bound_ctrl:1
	v_add_f32_dpp v225, v225, v225 quad_perm:[2,3,0,1] row_mask:0xf bank_mask:0xf bound_ctrl:1
	v_add_f32_dpp v226, v226, v226 quad_perm:[2,3,0,1] row_mask:0xf bank_mask:0xf bound_ctrl:1
	v_add_f32_dpp v227, v227, v227 quad_perm:[2,3,0,1] row_mask:0xf bank_mask:0xf bound_ctrl:1
	v_add_f32_dpp v228, v228, v228 quad_perm:[2,3,0,1] row_mask:0xf bank_mask:0xf bound_ctrl:1
	v_add_f32_dpp v229, v229, v229 quad_perm:[2,3,0,1] row_mask:0xf bank_mask:0xf bound_ctrl:1
	v_add_f32_dpp v230, v230, v230 quad_perm:[2,3,0,1] row_mask:0xf bank_mask:0xf bound_ctrl:1
	v_add_f32_dpp v231, v231, v231 quad_perm:[2,3,0,1] row_mask:0xf bank_mask:0xf bound_ctrl:1
	v_add_f32_dpp v224, v224, v224 row_half_mirror row_mask:0xf bank_mask:0xf bound_ctrl:1
	v_add_f32_dpp v225, v225, v225 row_half_mirror row_mask:0xf bank_mask:0xf bound_ctrl:1
	v_add_f32_dpp v226, v226, v226 row_half_mirror row_mask:0xf bank_mask:0xf bound_ctrl:1
	v_add_f32_dpp v227, v227, v227 row_half_mirror row_mask:0xf bank_mask:0xf bound_ctrl:1
	v_add_f32_dpp v228, v228, v228 row_half_mirror row_mask:0xf bank_mask:0xf bound_ctrl:1
	v_add_f32_dpp v229, v229, v229 row_half_mirror row_mask:0xf bank_mask:0xf bound_ctrl:1
	v_add_f32_dpp v230, v230, v230 row_half_mirror row_mask:0xf bank_mask:0xf bound_ctrl:1
	v_add_f32_dpp v231, v231, v231 row_half_mirror row_mask:0xf bank_mask:0xf bound_ctrl:1
	v_add_f32_dpp v224, v224, v224 row_mirror row_mask:0xf bank_mask:0xf bound_ctrl:1
	v_add_f32_dpp v225, v225, v225 row_mirror row_mask:0xf bank_mask:0xf bound_ctrl:1
	v_add_f32_dpp v226, v226, v226 row_mirror row_mask:0xf bank_mask:0xf bound_ctrl:1
	v_add_f32_dpp v227, v227, v227 row_mirror row_mask:0xf bank_mask:0xf bound_ctrl:1
	v_add_f32_dpp v228, v228, v228 row_mirror row_mask:0xf bank_mask:0xf bound_ctrl:1
	v_add_f32_dpp v229, v229, v229 row_mirror row_mask:0xf bank_mask:0xf bound_ctrl:1
	v_add_f32_dpp v230, v230, v230 row_mirror row_mask:0xf bank_mask:0xf bound_ctrl:1
	v_add_f32_dpp v231, v231, v231 row_mirror row_mask:0xf bank_mask:0xf bound_ctrl:1
	v_add_f32_dpp v224, v224, v224 row_bcast:15 row_mask:0xa bank_mask:0xf
	v_add_f32_dpp v225, v225, v225 row_bcast:15 row_mask:0xa bank_mask:0xf
	v_add_f32_dpp v226, v226, v226 row_bcast:15 row_mask:0xa bank_mask:0xf
	v_add_f32_dpp v227, v227, v227 row_bcast:15 row_mask:0xa bank_mask:0xf
	v_add_f32_dpp v228, v228, v228 row_bcast:15 row_mask:0xa bank_mask:0xf
	v_add_f32_dpp v229, v229, v229 row_bcast:15 row_mask:0xa bank_mask:0xf
	v_add_f32_dpp v230, v230, v230 row_bcast:15 row_mask:0xa bank_mask:0xf
	v_add_f32_dpp v231, v231, v231 row_bcast:15 row_mask:0xa bank_mask:0xf
	v_add_f32_dpp v224, v224, v224 row_bcast:31 row_mask:0xc bank_mask:0xf
	v_add_f32_dpp v225, v225, v225 row_bcast:31 row_mask:0xc bank_mask:0xf
	v_add_f32_dpp v226, v226, v226 row_bcast:31 row_mask:0xc bank_mask:0xf
	v_add_f32_dpp v227, v227, v227 row_bcast:31 row_mask:0xc bank_mask:0xf
	v_add_f32_dpp v228, v228, v228 row_bcast:31 row_mask:0xc bank_mask:0xf
	v_add_f32_dpp v229, v229, v229 row_bcast:31 row_mask:0xc bank_mask:0xf
	v_add_f32_dpp v230, v230, v230 row_bcast:31 row_mask:0xc bank_mask:0xf
	v_add_f32_dpp v231, v231, v231 row_bcast:31 row_mask:0xc bank_mask:0xf
	v_readlane_b32 s4, v224, 63
	v_readlane_b32 s5, v225, 63
	v_readlane_b32 s26, v226, 63
	v_readlane_b32 s27, v227, 63
	v_readlane_b32 s44, v228, 63
	v_readlane_b32 s45, v229, 63
	v_readlane_b32 s46, v230, 63
	v_readlane_b32 s47, v231, 63
	v_add_f32_e32 v200, s4, v232
	v_add_f32_e32 v201, s5, v233
	v_add_f32_e32 v202, s26, v234
	v_add_f32_e32 v203, s27, v235
	v_add_f32_e32 v204, s44, v236
	v_add_f32_e32 v205, s45, v237
	v_add_f32_e32 v206, s46, v238
	v_add_f32_e32 v207, s47, v239
	s_lshl_b32 s30, s95, 2
	s_add_i32 s30, s30, 0xfffd0000
	v_lshl_add_u32 v38, v108, 5, s30
	ds_write_b128 v38, v[176:179]
	ds_write_b128 v38, v[180:183] offset:16
	ds_write_b128 v38, v[184:187] offset:2048
	ds_write_b128 v38, v[188:191] offset:2064
	s_mov_b64 s[44:45], exec
	s_mov_b64 exec, s[40:41]
	v_lshl_add_u32 v39, v108, 5, s95
	ds_write_b128 v39, v[192:195]
	ds_write_b128 v39, v[196:199] offset:16
	s_mov_b64 exec, s[44:45]
	v_lshrrev_b32_e32 v40, 4, v108
	v_and_b32_e32 v41, 7, v108
	v_lshlrev_b32_e32 v42, 5, v40
	v_lshl_add_u32 v42, v41, 2, v42
	v_add_u32_e32 v43, s30, v42
	v_add_u32_e32 v42, s95, v42
	v_and_b32_e32 v41, 15, v108
	v_lshlrev_b32_e32 v35, 8, v40
	v_lshl_add_u32 v35, v41, 2, v35
	v_add_u32_e32 v35, 0x9080, v35
	v_mov_b32_e32 v208, 0
	v_mov_b32_e32 v209, 0
	v_mov_b32_e32 v210, 0
	v_mov_b32_e32 v211, 0
	v_mov_b32_e32 v212, 0
	v_mov_b32_e32 v213, 0
	v_mov_b32_e32 v214, 0
	v_mov_b32_e32 v215, 0
	v_mov_b32_e32 v216, 0
	v_mov_b32_e32 v217, 0
	v_mov_b32_e32 v218, 0
	v_mov_b32_e32 v219, 0
	v_mov_b32_e32 v220, 0
	v_mov_b32_e32 v221, 0
	v_mov_b32_e32 v222, 0
	v_mov_b32_e32 v223, 0
	s_waitcnt lgkmcnt(0)
	ds_read_b32 v60, v43 offset:0
	ds_read_b32 v61, v35 offset:0
	ds_read_b32 v62, v35 offset:64
	ds_read_b32 v63, v35 offset:128
	ds_read_b32 v64, v35 offset:192
	ds_read_b32 v65, v43 offset:128
	ds_read_b32 v66, v35 offset:1024
	ds_read_b32 v67, v35 offset:1088
	ds_read_b32 v68, v35 offset:1152
	ds_read_b32 v69, v35 offset:1216
	ds_read_b32 v70, v43 offset:256
	ds_read_b32 v71, v35 offset:2048
	ds_read_b32 v72, v35 offset:2112
	ds_read_b32 v73, v35 offset:2176
	ds_read_b32 v74, v35 offset:2240
	s_waitcnt lgkmcnt(10)
	v_mfma_f32_16x16x4_f32 v[208:211], v60, v61, v[208:211]
	v_mfma_f32_16x16x4_f32 v[212:215], v60, v62, v[212:215]
	v_mfma_f32_16x16x4_f32 v[216:219], v60, v63, v[216:219]
	v_mfma_f32_16x16x4_f32 v[220:223], v60, v64, v[220:223]
	ds_read_b32 v60, v43 offset:384
	ds_read_b32 v61, v35 offset:3072
	ds_read_b32 v62, v35 offset:3136
	ds_read_b32 v63, v35 offset:3200
	ds_read_b32 v64, v35 offset:3264
	s_waitcnt lgkmcnt(10)
	v_mfma_f32_16x16x4_f32 v[208:211], v65, v66, v[208:211]
	v_mfma_f32_16x16x4_f32 v[212:215], v65, v67, v[212:215]
	v_mfma_f32_16x16x4_f32 v[216:219], v65, v68, v[216:219]
	v_mfma_f32_16x16x4_f32 v[220:223], v65, v69, v[220:223]
	ds_read_b32 v65, v43 offset:512
	ds_read_b32 v66, v35 offset:4096
	ds_read_b32 v67, v35 offset:4160
	ds_read_b32 v68, v35 offset:4224
	ds_read_b32 v69, v35 offset:4288
	s_waitcnt lgkmcnt(10)
	v_mfma_f32_16x16x4_f32 v[208:211], v70, v71, v[208:211]
	v_mfma_f32_16x16x4_f32 v[212:215], v70, v72, v[212:215]
	v_mfma_f32_16x16x4_f32 v[216:219], v70, v73, v[216:219]
	v_mfma_f32_16x16x4_f32 v[220:223], v70, v74, v[220:223]
	ds_read_b32 v70, v43 offset:640
	ds_read_b32 v71, v35 offset:5120
	ds_read_b32 v72, v35 offset:5184
	ds_read_b32 v73, v35 offset:5248
	ds_read_b32 v74, v35 offset:5312
	s_waitcnt lgkmcnt(10)
	v_mfma_f32_16x16x4_f32 v[208:211], v60, v61, v[208:211]
	v_mfma_f32_16x16x4_f32 v[212:215], v60, v62, v[212:215]
	v_mfma_f32_16x16x4_f32 v[216:219], v60, v63, v[216:219]
	v_mfma_f32_16x16x4_f32 v[220:223], v60, v64, v[220:223]
	ds_read_b32 v60, v43 offset:768
	ds_read_b32 v61, v35 offset:6144
	ds_read_b32 v62, v35 offset:6208
	ds_read_b32 v63, v35 offset:6272
	ds_read_b32 v64, v35 offset:6336
	s_waitcnt lgkmcnt(10)
	v_mfma_f32_16x16x4_f32 v[208:211], v65, v66, v[208:211]
	v_mfma_f32_16x16x4_f32 v[212:215], v65, v67, v[212:215]
	v_mfma_f32_16x16x4_f32 v[216:219], v65, v68, v[216:219]
	v_mfma_f32_16x16x4_f32 v[220:223], v65, v69, v[220:223]
	ds_read_b32 v65, v43 offset:896
	ds_read_b32 v66, v35 offset:7168
	ds_read_b32 v67, v35 offset:7232
	ds_read_b32 v68, v35 offset:7296
	ds_read_b32 v69, v35 offset:7360
	s_waitcnt lgkmcnt(10)
	v_mfma_f32_16x16x4_f32 v[208:211], v70, v71, v[208:211]
	v_mfma_f32_16x16x4_f32 v[212:215], v70, v72, v[212:215]
	v_mfma_f32_16x16x4_f32 v[216:219], v70, v73, v[216:219]
	v_mfma_f32_16x16x4_f32 v[220:223], v70, v74, v[220:223]
	ds_read_b32 v70, v43 offset:1024
	ds_read_b32 v71, v35 offset:8192
	ds_read_b32 v72, v35 offset:8256
	ds_read_b32 v73, v35 offset:8320
	ds_read_b32 v74, v35 offset:8384
	s_waitcnt lgkmcnt(10)
	v_mfma_f32_16x16x4_f32 v[208:211], v60, v61, v[208:211]
	v_mfma_f32_16x16x4_f32 v[212:215], v60, v62, v[212:215]
	v_mfma_f32_16x16x4_f32 v[216:219], v60, v63, v[216:219]
	v_mfma_f32_16x16x4_f32 v[220:223], v60, v64, v[220:223]
	ds_read_b32 v60, v43 offset:1152
	ds_read_b32 v61, v35 offset:9216
	ds_read_b32 v62, v35 offset:9280
	ds_read_b32 v63, v35 offset:9344
	ds_read_b32 v64, v35 offset:9408
	s_waitcnt lgkmcnt(10)
	v_mfma_f32_16x16x4_f32 v[208:211], v65, v66, v[208:211]
	v_mfma_f32_16x16x4_f32 v[212:215], v65, v67, v[212:215]
	v_mfma_f32_16x16x4_f32 v[216:219], v65, v68, v[216:219]
	v_mfma_f32_16x16x4_f32 v[220:223], v65, v69, v[220:223]
	ds_read_b32 v65, v43 offset:1280
	ds_read_b32 v66, v35 offset:10240
	ds_read_b32 v67, v35 offset:10304
	ds_read_b32 v68, v35 offset:10368
	ds_read_b32 v69, v35 offset:10432
	s_waitcnt lgkmcnt(10)
	v_mfma_f32_16x16x4_f32 v[208:211], v70, v71, v[208:211]
	v_mfma_f32_16x16x4_f32 v[212:215], v70, v72, v[212:215]
	v_mfma_f32_16x16x4_f32 v[216:219], v70, v73, v[216:219]
	v_mfma_f32_16x16x4_f32 v[220:223], v70, v74, v[220:223]
	ds_read_b32 v70, v43 offset:1408
	ds_read_b32 v71, v35 offset:11264
	ds_read_b32 v72, v35 offset:11328
	ds_read_b32 v73, v35 offset:11392
	ds_read_b32 v74, v35 offset:11456
	s_waitcnt lgkmcnt(10)
	v_mfma_f32_16x16x4_f32 v[208:211], v60, v61, v[208:211]
	v_mfma_f32_16x16x4_f32 v[212:215], v60, v62, v[212:215]
	v_mfma_f32_16x16x4_f32 v[216:219], v60, v63, v[216:219]
	v_mfma_f32_16x16x4_f32 v[220:223], v60, v64, v[220:223]
	ds_read_b32 v60, v43 offset:1536
	ds_read_b32 v61, v35 offset:12288
	ds_read_b32 v62, v35 offset:12352
	ds_read_b32 v63, v35 offset:12416
	ds_read_b32 v64, v35 offset:12480
	s_waitcnt lgkmcnt(10)
	v_mfma_f32_16x16x4_f32 v[208:211], v65, v66, v[208:211]
	v_mfma_f32_16x16x4_f32 v[212:215], v65, v67, v[212:215]
	v_mfma_f32_16x16x4_f32 v[216:219], v65, v68, v[216:219]
	v_mfma_f32_16x16x4_f32 v[220:223], v65, v69, v[220:223]
	ds_read_b32 v65, v43 offset:1664
	ds_read_b32 v66, v35 offset:13312
	ds_read_b32 v67, v35 offset:13376
	ds_read_b32 v68, v35 offset:13440
	ds_read_b32 v69, v35 offset:13504
	s_waitcnt lgkmcnt(10)
	v_mfma_f32_16x16x4_f32 v[208:211], v70, v71, v[208:211]
	v_mfma_f32_16x16x4_f32 v[212:215], v70, v72, v[212:215]
	v_mfma_f32_16x16x4_f32 v[216:219], v70, v73, v[216:219]
	v_mfma_f32_16x16x4_f32 v[220:223], v70, v74, v[220:223]
	ds_read_b32 v70, v43 offset:1792
	ds_read_b32 v71, v35 offset:14336
	ds_read_b32 v72, v35 offset:14400
	ds_read_b32 v73, v35 offset:14464
	ds_read_b32 v74, v35 offset:14528
	s_waitcnt lgkmcnt(10)
	v_mfma_f32_16x16x4_f32 v[208:211], v60, v61, v[208:211]
	v_mfma_f32_16x16x4_f32 v[212:215], v60, v62, v[212:215]
	v_mfma_f32_16x16x4_f32 v[216:219], v60, v63, v[216:219]
	v_mfma_f32_16x16x4_f32 v[220:223], v60, v64, v[220:223]
	ds_read_b32 v60, v43 offset:1920
	ds_read_b32 v61, v35 offset:15360
	ds_read_b32 v62, v35 offset:15424
	ds_read_b32 v63, v35 offset:15488
	ds_read_b32 v64, v35 offset:15552
	s_waitcnt lgkmcnt(10)
	v_mfma_f32_16x16x4_f32 v[208:211], v65, v66, v[208:211]
	v_mfma_f32_16x16x4_f32 v[212:215], v65, v67, v[212:215]
	v_mfma_f32_16x16x4_f32 v[216:219], v65, v68, v[216:219]
	v_mfma_f32_16x16x4_f32 v[220:223], v65, v69, v[220:223]
	ds_read_b32 v65, v43 offset:2048
	ds_read_b32 v66, v35 offset:16384
	ds_read_b32 v67, v35 offset:16448
	ds_read_b32 v68, v35 offset:16512
	ds_read_b32 v69, v35 offset:16576
	s_waitcnt lgkmcnt(10)
	v_mfma_f32_16x16x4_f32 v[208:211], v70, v71, v[208:211]
	v_mfma_f32_16x16x4_f32 v[212:215], v70, v72, v[212:215]
	v_mfma_f32_16x16x4_f32 v[216:219], v70, v73, v[216:219]
	v_mfma_f32_16x16x4_f32 v[220:223], v70, v74, v[220:223]
	ds_read_b32 v70, v43 offset:2176
	ds_read_b32 v71, v35 offset:17408
	ds_read_b32 v72, v35 offset:17472
	ds_read_b32 v73, v35 offset:17536
	ds_read_b32 v74, v35 offset:17600
	s_waitcnt lgkmcnt(10)
	v_mfma_f32_16x16x4_f32 v[208:211], v60, v61, v[208:211]
	v_mfma_f32_16x16x4_f32 v[212:215], v60, v62, v[212:215]
	v_mfma_f32_16x16x4_f32 v[216:219], v60, v63, v[216:219]
	v_mfma_f32_16x16x4_f32 v[220:223], v60, v64, v[220:223]
	ds_read_b32 v60, v43 offset:2304
	ds_read_b32 v61, v35 offset:18432
	ds_read_b32 v62, v35 offset:18496
	ds_read_b32 v63, v35 offset:18560
	ds_read_b32 v64, v35 offset:18624
	s_waitcnt lgkmcnt(10)
	v_mfma_f32_16x16x4_f32 v[208:211], v65, v66, v[208:211]
	v_mfma_f32_16x16x4_f32 v[212:215], v65, v67, v[212:215]
	v_mfma_f32_16x16x4_f32 v[216:219], v65, v68, v[216:219]
	v_mfma_f32_16x16x4_f32 v[220:223], v65, v69, v[220:223]
	ds_read_b32 v65, v43 offset:2432
	ds_read_b32 v66, v35 offset:19456
	ds_read_b32 v67, v35 offset:19520
	ds_read_b32 v68, v35 offset:19584
	ds_read_b32 v69, v35 offset:19648
	s_waitcnt lgkmcnt(10)
	v_mfma_f32_16x16x4_f32 v[208:211], v70, v71, v[208:211]
	v_mfma_f32_16x16x4_f32 v[212:215], v70, v72, v[212:215]
	v_mfma_f32_16x16x4_f32 v[216:219], v70, v73, v[216:219]
	v_mfma_f32_16x16x4_f32 v[220:223], v70, v74, v[220:223]
	ds_read_b32 v70, v43 offset:2560
	ds_read_b32 v71, v35 offset:20480
	ds_read_b32 v72, v35 offset:20544
	ds_read_b32 v73, v35 offset:20608
	ds_read_b32 v74, v35 offset:20672
	s_waitcnt lgkmcnt(10)
	v_mfma_f32_16x16x4_f32 v[208:211], v60, v61, v[208:211]
	v_mfma_f32_16x16x4_f32 v[212:215], v60, v62, v[212:215]
	v_mfma_f32_16x16x4_f32 v[216:219], v60, v63, v[216:219]
	v_mfma_f32_16x16x4_f32 v[220:223], v60, v64, v[220:223]
	ds_read_b32 v60, v43 offset:2688
	ds_read_b32 v61, v35 offset:21504
	ds_read_b32 v62, v35 offset:21568
	ds_read_b32 v63, v35 offset:21632
	ds_read_b32 v64, v35 offset:21696
	s_waitcnt lgkmcnt(10)
	v_mfma_f32_16x16x4_f32 v[208:211], v65, v66, v[208:211]
	v_mfma_f32_16x16x4_f32 v[212:215], v65, v67, v[212:215]
	v_mfma_f32_16x16x4_f32 v[216:219], v65, v68, v[216:219]
	v_mfma_f32_16x16x4_f32 v[220:223], v65, v69, v[220:223]
	ds_read_b32 v65, v43 offset:2816
	ds_read_b32 v66, v35 offset:22528
	ds_read_b32 v67, v35 offset:22592
	ds_read_b32 v68, v35 offset:22656
	ds_read_b32 v69, v35 offset:22720
	s_waitcnt lgkmcnt(10)
	v_mfma_f32_16x16x4_f32 v[208:211], v70, v71, v[208:211]
	v_mfma_f32_16x16x4_f32 v[212:215], v70, v72, v[212:215]
	v_mfma_f32_16x16x4_f32 v[216:219], v70, v73, v[216:219]
	v_mfma_f32_16x16x4_f32 v[220:223], v70, v74, v[220:223]
	ds_read_b32 v70, v43 offset:2944
	ds_read_b32 v71, v35 offset:23552
	ds_read_b32 v72, v35 offset:23616
	ds_read_b32 v73, v35 offset:23680
	ds_read_b32 v74, v35 offset:23744
	s_waitcnt lgkmcnt(10)
	v_mfma_f32_16x16x4_f32 v[208:211], v60, v61, v[208:211]
	v_mfma_f32_16x16x4_f32 v[212:215], v60, v62, v[212:215]
	v_mfma_f32_16x16x4_f32 v[216:219], v60, v63, v[216:219]
	v_mfma_f32_16x16x4_f32 v[220:223], v60, v64, v[220:223]
	ds_read_b32 v60, v43 offset:3072
	ds_read_b32 v61, v35 offset:24576
	ds_read_b32 v62, v35 offset:24640
	ds_read_b32 v63, v35 offset:24704
	ds_read_b32 v64, v35 offset:24768
	s_waitcnt lgkmcnt(10)
	v_mfma_f32_16x16x4_f32 v[208:211], v65, v66, v[208:211]
	v_mfma_f32_16x16x4_f32 v[212:215], v65, v67, v[212:215]
	v_mfma_f32_16x16x4_f32 v[216:219], v65, v68, v[216:219]
	v_mfma_f32_16x16x4_f32 v[220:223], v65, v69, v[220:223]
	ds_read_b32 v65, v43 offset:3200
	ds_read_b32 v66, v35 offset:25600
	ds_read_b32 v67, v35 offset:25664
	ds_read_b32 v68, v35 offset:25728
	ds_read_b32 v69, v35 offset:25792
	s_waitcnt lgkmcnt(10)
	v_mfma_f32_16x16x4_f32 v[208:211], v70, v71, v[208:211]
	v_mfma_f32_16x16x4_f32 v[212:215], v70, v72, v[212:215]
	v_mfma_f32_16x16x4_f32 v[216:219], v70, v73, v[216:219]
	v_mfma_f32_16x16x4_f32 v[220:223], v70, v74, v[220:223]
	ds_read_b32 v70, v43 offset:3328
	ds_read_b32 v71, v35 offset:26624
	ds_read_b32 v72, v35 offset:26688
	ds_read_b32 v73, v35 offset:26752
	ds_read_b32 v74, v35 offset:26816
	s_waitcnt lgkmcnt(10)
	v_mfma_f32_16x16x4_f32 v[208:211], v60, v61, v[208:211]
	v_mfma_f32_16x16x4_f32 v[212:215], v60, v62, v[212:215]
	v_mfma_f32_16x16x4_f32 v[216:219], v60, v63, v[216:219]
	v_mfma_f32_16x16x4_f32 v[220:223], v60, v64, v[220:223]
	ds_read_b32 v60, v43 offset:3456
	ds_read_b32 v61, v35 offset:27648
	ds_read_b32 v62, v35 offset:27712
	ds_read_b32 v63, v35 offset:27776
	ds_read_b32 v64, v35 offset:27840
	s_waitcnt lgkmcnt(10)
	v_mfma_f32_16x16x4_f32 v[208:211], v65, v66, v[208:211]
	v_mfma_f32_16x16x4_f32 v[212:215], v65, v67, v[212:215]
	v_mfma_f32_16x16x4_f32 v[216:219], v65, v68, v[216:219]
	v_mfma_f32_16x16x4_f32 v[220:223], v65, v69, v[220:223]
	ds_read_b32 v65, v43 offset:3584
	ds_read_b32 v66, v35 offset:28672
	ds_read_b32 v67, v35 offset:28736
	ds_read_b32 v68, v35 offset:28800
	ds_read_b32 v69, v35 offset:28864
	s_waitcnt lgkmcnt(10)
	v_mfma_f32_16x16x4_f32 v[208:211], v70, v71, v[208:211]
	v_mfma_f32_16x16x4_f32 v[212:215], v70, v72, v[212:215]
	v_mfma_f32_16x16x4_f32 v[216:219], v70, v73, v[216:219]
	v_mfma_f32_16x16x4_f32 v[220:223], v70, v74, v[220:223]
	ds_read_b32 v70, v43 offset:3712
	ds_read_b32 v71, v35 offset:29696
	ds_read_b32 v72, v35 offset:29760
	ds_read_b32 v73, v35 offset:29824
	ds_read_b32 v74, v35 offset:29888
	s_waitcnt lgkmcnt(10)
	v_mfma_f32_16x16x4_f32 v[208:211], v60, v61, v[208:211]
	v_mfma_f32_16x16x4_f32 v[212:215], v60, v62, v[212:215]
	v_mfma_f32_16x16x4_f32 v[216:219], v60, v63, v[216:219]
	v_mfma_f32_16x16x4_f32 v[220:223], v60, v64, v[220:223]
	ds_read_b32 v60, v43 offset:3840
	ds_read_b32 v61, v35 offset:30720
	ds_read_b32 v62, v35 offset:30784
	ds_read_b32 v63, v35 offset:30848
	ds_read_b32 v64, v35 offset:30912
	s_waitcnt lgkmcnt(10)
	v_mfma_f32_16x16x4_f32 v[208:211], v65, v66, v[208:211]
	v_mfma_f32_16x16x4_f32 v[212:215], v65, v67, v[212:215]
	v_mfma_f32_16x16x4_f32 v[216:219], v65, v68, v[216:219]
	v_mfma_f32_16x16x4_f32 v[220:223], v65, v69, v[220:223]
	ds_read_b32 v65, v43 offset:3968
	ds_read_b32 v66, v35 offset:31744
	ds_read_b32 v67, v35 offset:31808
	ds_read_b32 v68, v35 offset:31872
	ds_read_b32 v69, v35 offset:31936
	s_waitcnt lgkmcnt(10)
	v_mfma_f32_16x16x4_f32 v[208:211], v70, v71, v[208:211]
	v_mfma_f32_16x16x4_f32 v[212:215], v70, v72, v[212:215]
	v_mfma_f32_16x16x4_f32 v[216:219], v70, v73, v[216:219]
	v_mfma_f32_16x16x4_f32 v[220:223], v70, v74, v[220:223]
	ds_read_b32 v70, v42 offset:0
	ds_read_b32 v71, v35 offset:32768
	ds_read_b32 v72, v35 offset:32832
	ds_read_b32 v73, v35 offset:32896
	ds_read_b32 v74, v35 offset:32960
	s_waitcnt lgkmcnt(10)
	v_mfma_f32_16x16x4_f32 v[208:211], v60, v61, v[208:211]
	v_mfma_f32_16x16x4_f32 v[212:215], v60, v62, v[212:215]
	v_mfma_f32_16x16x4_f32 v[216:219], v60, v63, v[216:219]
	v_mfma_f32_16x16x4_f32 v[220:223], v60, v64, v[220:223]
	ds_read_b32 v60, v42 offset:128
	ds_read_b32 v61, v35 offset:33792
	ds_read_b32 v62, v35 offset:33856
	ds_read_b32 v63, v35 offset:33920
	ds_read_b32 v64, v35 offset:33984
	s_waitcnt lgkmcnt(10)
	v_mfma_f32_16x16x4_f32 v[208:211], v65, v66, v[208:211]
	v_mfma_f32_16x16x4_f32 v[212:215], v65, v67, v[212:215]
	v_mfma_f32_16x16x4_f32 v[216:219], v65, v68, v[216:219]
	v_mfma_f32_16x16x4_f32 v[220:223], v65, v69, v[220:223]
	s_waitcnt lgkmcnt(5)
	v_mfma_f32_16x16x4_f32 v[208:211], v70, v71, v[208:211]
	v_mfma_f32_16x16x4_f32 v[212:215], v70, v72, v[212:215]
	v_mfma_f32_16x16x4_f32 v[216:219], v70, v73, v[216:219]
	v_mfma_f32_16x16x4_f32 v[220:223], v70, v74, v[220:223]
	s_waitcnt lgkmcnt(0)
	v_mfma_f32_16x16x4_f32 v[208:211], v60, v61, v[208:211]
	v_mfma_f32_16x16x4_f32 v[212:215], v60, v62, v[212:215]
	v_mfma_f32_16x16x4_f32 v[216:219], v60, v63, v[216:219]
	v_mfma_f32_16x16x4_f32 v[220:223], v60, v64, v[220:223]
	v_bfe_u32 v38, v108, 4, 1
	v_cmp_eq_u32_e64 s[44:45], 1, v38
	s_lshl_b32 s26, s16, 11
	s_mov_b32 s27, 0
	v_mul_u32_u24_e32 v38, 0x1fe0, v38
	v_mov_b32_e32 v39, 0
	v_cndmask_b32_e64 v224, v200, v204, s[44:45]
	v_cndmask_b32_e64 v225, v201, v205, s[44:45]
	v_cndmask_b32_e64 v226, v202, v206, s[44:45]
	v_cndmask_b32_e64 v227, v203, v207, s[44:45]
	v_lshl_add_u64 v[40:41], v[8:9], 0, v[38:39]
	v_lshl_add_u64 v[40:41], v[40:41], 0, s[26:27]
	s_mov_b64 s[26:27], 0x1000
	v_lshl_add_u64 v[42:43], v[40:41], 0, s[26:27]
	s_mov_b64 s[46:47], exec
	s_mov_b32 exec_hi, 0
	s_nop 7
	s_nop 7
	v_div_scale_f32 v60, s[26:27], v224, v224, v208
	v_rcp_f32_e32 v61, v60
	s_nop 0
	v_fma_f32 v62, -v60, v61, 1.0
	v_fmac_f32_e32 v61, v62, v61
	v_div_scale_f32 v62, vcc, v208, v224, v208
	v_mul_f32_e32 v63, v62, v61
	v_fma_f32 v64, -v60, v63, v62
	v_fmac_f32_e32 v63, v64, v61
	v_fma_f32 v60, -v60, v63, v62
	v_div_fmas_f32 v60, v60, v61, v63
	v_div_fixup_f32 v60, v60, v224, v208
	v_bfe_u32 v61, v60, 16, 1
	v_add3_u32 v61, v60, v61, s48
	flat_store_short_d16_hi v[40:41], v61 offset:0
	v_div_scale_f32 v60, s[26:27], v225, v225, v209
	v_rcp_f32_e32 v61, v60
	s_nop 0
	v_fma_f32 v62, -v60, v61, 1.0
	v_fmac_f32_e32 v61, v62, v61
	v_div_scale_f32 v62, vcc, v209, v225, v209
	v_mul_f32_e32 v63, v62, v61
	v_fma_f32 v64, -v60, v63, v62
	v_fmac_f32_e32 v63, v64, v61
	v_fma_f32 v60, -v60, v63, v62
	v_div_fmas_f32 v60, v60, v61, v63
	v_div_fixup_f32 v60, v60, v225, v209
	v_bfe_u32 v61, v60, 16, 1
	v_add3_u32 v61, v60, v61, s48
	flat_store_short_d16_hi v[40:41], v61 offset:2048
	v_div_scale_f32 v60, s[26:27], v226, v226, v210
	v_rcp_f32_e32 v61, v60
	s_nop 0
	v_fma_f32 v62, -v60, v61, 1.0
	v_fmac_f32_e32 v61, v62, v61
	v_div_scale_f32 v62, vcc, v210, v226, v210
	v_mul_f32_e32 v63, v62, v61
	v_fma_f32 v64, -v60, v63, v62
	v_fmac_f32_e32 v63, v64, v61
	v_fma_f32 v60, -v60, v63, v62
	v_div_fmas_f32 v60, v60, v61, v63
	v_div_fixup_f32 v60, v60, v226, v210
	v_bfe_u32 v61, v60, 16, 1
	v_add3_u32 v61, v60, v61, s48
	flat_store_short_d16_hi v[42:43], v61 offset:0
	v_div_scale_f32 v60, s[26:27], v227, v227, v211
	v_rcp_f32_e32 v61, v60
	s_nop 0
	v_fma_f32 v62, -v60, v61, 1.0
	v_fmac_f32_e32 v61, v62, v61
	v_div_scale_f32 v62, vcc, v211, v227, v211
	v_mul_f32_e32 v63, v62, v61
	v_fma_f32 v64, -v60, v63, v62
	v_fmac_f32_e32 v63, v64, v61
	v_fma_f32 v60, -v60, v63, v62
	v_div_fmas_f32 v60, v60, v61, v63
	v_div_fixup_f32 v60, v60, v227, v211
	v_bfe_u32 v61, v60, 16, 1
	v_add3_u32 v61, v60, v61, s48
	flat_store_short_d16_hi v[42:43], v61 offset:2048
	v_div_scale_f32 v60, s[26:27], v224, v224, v212
	v_rcp_f32_e32 v61, v60
	s_nop 0
	v_fma_f32 v62, -v60, v61, 1.0
	v_fmac_f32_e32 v61, v62, v61
	v_div_scale_f32 v62, vcc, v212, v224, v212
	v_mul_f32_e32 v63, v62, v61
	v_fma_f32 v64, -v60, v63, v62
	v_fmac_f32_e32 v63, v64, v61
	v_fma_f32 v60, -v60, v63, v62
	v_div_fmas_f32 v60, v60, v61, v63
	v_div_fixup_f32 v60, v60, v224, v212
	v_bfe_u32 v61, v60, 16, 1
	v_add3_u32 v61, v60, v61, s48
	flat_store_short_d16_hi v[40:41], v61 offset:32
	v_div_scale_f32 v60, s[26:27], v225, v225, v213
	v_rcp_f32_e32 v61, v60
	s_nop 0
	v_fma_f32 v62, -v60, v61, 1.0
	v_fmac_f32_e32 v61, v62, v61
	v_div_scale_f32 v62, vcc, v213, v225, v213
	v_mul_f32_e32 v63, v62, v61
	v_fma_f32 v64, -v60, v63, v62
	v_fmac_f32_e32 v63, v64, v61
	v_fma_f32 v60, -v60, v63, v62
	v_div_fmas_f32 v60, v60, v61, v63
	v_div_fixup_f32 v60, v60, v225, v213
	v_bfe_u32 v61, v60, 16, 1
	v_add3_u32 v61, v60, v61, s48
	flat_store_short_d16_hi v[40:41], v61 offset:2080
	v_div_scale_f32 v60, s[26:27], v226, v226, v214
	v_rcp_f32_e32 v61, v60
	s_nop 0
	v_fma_f32 v62, -v60, v61, 1.0
	v_fmac_f32_e32 v61, v62, v61
	v_div_scale_f32 v62, vcc, v214, v226, v214
	v_mul_f32_e32 v63, v62, v61
	v_fma_f32 v64, -v60, v63, v62
	v_fmac_f32_e32 v63, v64, v61
	v_fma_f32 v60, -v60, v63, v62
	v_div_fmas_f32 v60, v60, v61, v63
	v_div_fixup_f32 v60, v60, v226, v214
	v_bfe_u32 v61, v60, 16, 1
	v_add3_u32 v61, v60, v61, s48
	flat_store_short_d16_hi v[42:43], v61 offset:32
	v_div_scale_f32 v60, s[26:27], v227, v227, v215
	v_rcp_f32_e32 v61, v60
	s_nop 0
	v_fma_f32 v62, -v60, v61, 1.0
	v_fmac_f32_e32 v61, v62, v61
	v_div_scale_f32 v62, vcc, v215, v227, v215
	v_mul_f32_e32 v63, v62, v61
	v_fma_f32 v64, -v60, v63, v62
	v_fmac_f32_e32 v63, v64, v61
	v_fma_f32 v60, -v60, v63, v62
	v_div_fmas_f32 v60, v60, v61, v63
	v_div_fixup_f32 v60, v60, v227, v215
	v_bfe_u32 v61, v60, 16, 1
	v_add3_u32 v61, v60, v61, s48
	flat_store_short_d16_hi v[42:43], v61 offset:2080
	v_div_scale_f32 v60, s[26:27], v224, v224, v216
	v_rcp_f32_e32 v61, v60
	s_nop 0
	v_fma_f32 v62, -v60, v61, 1.0
	v_fmac_f32_e32 v61, v62, v61
	v_div_scale_f32 v62, vcc, v216, v224, v216
	v_mul_f32_e32 v63, v62, v61
	v_fma_f32 v64, -v60, v63, v62
	v_fmac_f32_e32 v63, v64, v61
	v_fma_f32 v60, -v60, v63, v62
	v_div_fmas_f32 v60, v60, v61, v63
	v_div_fixup_f32 v60, v60, v224, v216
	v_bfe_u32 v61, v60, 16, 1
	v_add3_u32 v61, v60, v61, s48
	flat_store_short_d16_hi v[40:41], v61 offset:64
	v_div_scale_f32 v60, s[26:27], v225, v225, v217
	v_rcp_f32_e32 v61, v60
	s_nop 0
	v_fma_f32 v62, -v60, v61, 1.0
	v_fmac_f32_e32 v61, v62, v61
	v_div_scale_f32 v62, vcc, v217, v225, v217
	v_mul_f32_e32 v63, v62, v61
	v_fma_f32 v64, -v60, v63, v62
	v_fmac_f32_e32 v63, v64, v61
	v_fma_f32 v60, -v60, v63, v62
	v_div_fmas_f32 v60, v60, v61, v63
	v_div_fixup_f32 v60, v60, v225, v217
	v_bfe_u32 v61, v60, 16, 1
	v_add3_u32 v61, v60, v61, s48
	flat_store_short_d16_hi v[40:41], v61 offset:2112
	v_div_scale_f32 v60, s[26:27], v226, v226, v218
	v_rcp_f32_e32 v61, v60
	s_nop 0
	v_fma_f32 v62, -v60, v61, 1.0
	v_fmac_f32_e32 v61, v62, v61
	v_div_scale_f32 v62, vcc, v218, v226, v218
	v_mul_f32_e32 v63, v62, v61
	v_fma_f32 v64, -v60, v63, v62
	v_fmac_f32_e32 v63, v64, v61
	v_fma_f32 v60, -v60, v63, v62
	v_div_fmas_f32 v60, v60, v61, v63
	v_div_fixup_f32 v60, v60, v226, v218
	v_bfe_u32 v61, v60, 16, 1
	v_add3_u32 v61, v60, v61, s48
	flat_store_short_d16_hi v[42:43], v61 offset:64
	v_div_scale_f32 v60, s[26:27], v227, v227, v219
	v_rcp_f32_e32 v61, v60
	s_nop 0
	v_fma_f32 v62, -v60, v61, 1.0
	v_fmac_f32_e32 v61, v62, v61
	v_div_scale_f32 v62, vcc, v219, v227, v219
	v_mul_f32_e32 v63, v62, v61
	v_fma_f32 v64, -v60, v63, v62
	v_fmac_f32_e32 v63, v64, v61
	v_fma_f32 v60, -v60, v63, v62
	v_div_fmas_f32 v60, v60, v61, v63
	v_div_fixup_f32 v60, v60, v227, v219
	v_bfe_u32 v61, v60, 16, 1
	v_add3_u32 v61, v60, v61, s48
	flat_store_short_d16_hi v[42:43], v61 offset:2112
	v_div_scale_f32 v60, s[26:27], v224, v224, v220
	v_rcp_f32_e32 v61, v60
	s_nop 0
	v_fma_f32 v62, -v60, v61, 1.0
	v_fmac_f32_e32 v61, v62, v61
	v_div_scale_f32 v62, vcc, v220, v224, v220
	v_mul_f32_e32 v63, v62, v61
	v_fma_f32 v64, -v60, v63, v62
	v_fmac_f32_e32 v63, v64, v61
	v_fma_f32 v60, -v60, v63, v62
	v_div_fmas_f32 v60, v60, v61, v63
	v_div_fixup_f32 v60, v60, v224, v220
	v_bfe_u32 v61, v60, 16, 1
	v_add3_u32 v61, v60, v61, s48
	flat_store_short_d16_hi v[40:41], v61 offset:96
	v_div_scale_f32 v60, s[26:27], v225, v225, v221
	v_rcp_f32_e32 v61, v60
	s_nop 0
	v_fma_f32 v62, -v60, v61, 1.0
	v_fmac_f32_e32 v61, v62, v61
	v_div_scale_f32 v62, vcc, v221, v225, v221
	v_mul_f32_e32 v63, v62, v61
	v_fma_f32 v64, -v60, v63, v62
	v_fmac_f32_e32 v63, v64, v61
	v_fma_f32 v60, -v60, v63, v62
	v_div_fmas_f32 v60, v60, v61, v63
	v_div_fixup_f32 v60, v60, v225, v221
	v_bfe_u32 v61, v60, 16, 1
	v_add3_u32 v61, v60, v61, s48
	flat_store_short_d16_hi v[40:41], v61 offset:2144
	v_div_scale_f32 v60, s[26:27], v226, v226, v222
	v_rcp_f32_e32 v61, v60
	s_nop 0
	v_fma_f32 v62, -v60, v61, 1.0
	v_fmac_f32_e32 v61, v62, v61
	v_div_scale_f32 v62, vcc, v222, v226, v222
	v_mul_f32_e32 v63, v62, v61
	v_fma_f32 v64, -v60, v63, v62
	v_fmac_f32_e32 v63, v64, v61
	v_fma_f32 v60, -v60, v63, v62
	v_div_fmas_f32 v60, v60, v61, v63
	v_div_fixup_f32 v60, v60, v226, v222
	v_bfe_u32 v61, v60, 16, 1
	v_add3_u32 v61, v60, v61, s48
	flat_store_short_d16_hi v[42:43], v61 offset:96
	v_div_scale_f32 v60, s[26:27], v227, v227, v223
	v_rcp_f32_e32 v61, v60
	s_nop 0
	v_fma_f32 v62, -v60, v61, 1.0
	v_fmac_f32_e32 v61, v62, v61
	v_div_scale_f32 v62, vcc, v223, v227, v223
	v_mul_f32_e32 v63, v62, v61
	v_fma_f32 v64, -v60, v63, v62
	v_fmac_f32_e32 v63, v64, v61
	v_fma_f32 v60, -v60, v63, v62
	v_div_fmas_f32 v60, v60, v61, v63
	v_div_fixup_f32 v60, v60, v227, v223
	v_bfe_u32 v61, v60, 16, 1
	v_add3_u32 v61, v60, v61, s48
	flat_store_short_d16_hi v[42:43], v61 offset:2144
	s_mov_b64 exec, s[46:47]
	s_add_i32 s15, s15, s74
	s_cmpk_gt_i32 s15, 0xff
	s_waitcnt lgkmcnt(0)
	s_barrier
	s_cbranch_scc0 .LBB0_689
